# static s_setprio 1 for waves 4-7 inside the attention tile loops
# speedup vs baseline: 1.0060x; 1.0060x over previous
.LBB0_834:
	s_setprio 0
	s_lshl_b64 s[6:7], s[74:75], 11
	s_add_u32 s2, s94, s6
	s_nop 1
	v_rcp_f32_e32 v4, v62
	s_addc_u32 s6, s95, s7
	s_add_u32 s2, s2, s3
	s_addc_u32 s3, s6, 0
	v_lshlrev_b32_e32 v0, 1, v136
	v_lshl_add_u64 v[2:3], s[2:3], 0, v[0:1]
	v_lshlrev_b32_e32 v0, 13, v135
	v_rcp_f32_e32 v5, v63
	v_lshl_add_u64 v[2:3], v[2:3], 0, v[0:1]
	v_mul_f32_e32 v0, v32, v4
	v_cvt_pk_bf16_f32 v0, v0, s0
	global_store_short v[2:3], v0, off offset:1024
	v_mul_f32_e32 v0, v16, v4
	v_cvt_pk_bf16_f32 v0, v0, s0
	v_rcp_f32_e32 v6, v64
	global_store_short v[2:3], v0, off offset:1088
	v_mul_f32_e32 v0, v33, v5
	v_cvt_pk_bf16_f32 v0, v0, s0
	global_store_short v[2:3], v0, off offset:3072
	v_mul_f32_e32 v0, v17, v5
	v_cvt_pk_bf16_f32 v0, v0, s0
	s_movk_i32 s2, 0x1000
	v_rcp_f32_e32 v7, v65
	global_store_short v[2:3], v0, off offset:3136
	v_mul_f32_e32 v0, v34, v6
	v_add_co_u32_e32 v4, vcc, s2, v2
	v_cvt_pk_bf16_f32 v0, v0, s0
	s_nop 0
	v_addc_co_u32_e32 v5, vcc, 0, v3, vcc
	global_store_short v[4:5], v0, off offset:1024
	v_mul_f32_e32 v0, v18, v6
	v_cvt_pk_bf16_f32 v0, v0, s0
	v_rcp_f32_e32 v8, v66
	global_store_short v[4:5], v0, off offset:1088
	v_mul_f32_e32 v0, v35, v7
	v_cvt_pk_bf16_f32 v0, v0, s0
	global_store_short v[4:5], v0, off offset:3072
	v_mul_f32_e32 v0, v19, v7
	v_cvt_pk_bf16_f32 v0, v0, s0
	s_movk_i32 s2, 0x4000
	v_rcp_f32_e32 v9, v67
	global_store_short v[4:5], v0, off offset:3136
	v_mul_f32_e32 v0, v36, v8
	v_add_co_u32_e32 v4, vcc, s2, v2
	v_cvt_pk_bf16_f32 v0, v0, s0
	s_nop 0
	v_addc_co_u32_e32 v5, vcc, 0, v3, vcc
	global_store_short v[4:5], v0, off offset:1024
	v_mul_f32_e32 v0, v20, v8
	v_cvt_pk_bf16_f32 v0, v0, s0
	v_rcp_f32_e32 v10, v68
	global_store_short v[4:5], v0, off offset:1088
	v_mul_f32_e32 v0, v37, v9
	v_cvt_pk_bf16_f32 v0, v0, s0
	global_store_short v[4:5], v0, off offset:3072
	v_mul_f32_e32 v0, v21, v9
	v_cvt_pk_bf16_f32 v0, v0, s0
	s_movk_i32 s2, 0x5000
	v_rcp_f32_e32 v11, v69
	global_store_short v[4:5], v0, off offset:3136
	v_mul_f32_e32 v0, v38, v10
	v_add_co_u32_e32 v4, vcc, s2, v2
	v_cvt_pk_bf16_f32 v0, v0, s0
	s_nop 0
	v_addc_co_u32_e32 v5, vcc, 0, v3, vcc
	global_store_short v[4:5], v0, off offset:1024
	v_mul_f32_e32 v0, v22, v10
	v_cvt_pk_bf16_f32 v0, v0, s0
	v_rcp_f32_e32 v12, v70
	global_store_short v[4:5], v0, off offset:1088
	v_mul_f32_e32 v0, v39, v11
	v_cvt_pk_bf16_f32 v0, v0, s0
	global_store_short v[4:5], v0, off offset:3072
	v_mul_f32_e32 v0, v23, v11
	v_cvt_pk_bf16_f32 v0, v0, s0
	s_mov_b32 s2, 0x8000
	v_rcp_f32_e32 v13, v71
	global_store_short v[4:5], v0, off offset:3136
	v_mul_f32_e32 v0, v40, v12
	v_add_co_u32_e32 v4, vcc, s2, v2
	v_cvt_pk_bf16_f32 v0, v0, s0
	s_nop 0
	v_addc_co_u32_e32 v5, vcc, 0, v3, vcc
	global_store_short v[4:5], v0, off offset:1024
	v_mul_f32_e32 v0, v24, v12
	v_cvt_pk_bf16_f32 v0, v0, s0
	v_rcp_f32_e32 v14, v72
	global_store_short v[4:5], v0, off offset:1088
	v_mul_f32_e32 v0, v41, v13
	v_cvt_pk_bf16_f32 v0, v0, s0
	global_store_short v[4:5], v0, off offset:3072
	v_mul_f32_e32 v0, v25, v13
	v_cvt_pk_bf16_f32 v0, v0, s0
	s_mov_b32 s2, 0x9000
	v_rcp_f32_e32 v15, v73
	global_store_short v[4:5], v0, off offset:3136
	v_mul_f32_e32 v0, v42, v14
	v_add_co_u32_e32 v4, vcc, s2, v2
	v_cvt_pk_bf16_f32 v0, v0, s0
	s_nop 0
	v_addc_co_u32_e32 v5, vcc, 0, v3, vcc
	global_store_short v[4:5], v0, off offset:1024
	v_mul_f32_e32 v0, v26, v14
	v_cvt_pk_bf16_f32 v0, v0, s0
	v_rcp_f32_e32 v48, v74
	global_store_short v[4:5], v0, off offset:1088
	v_mul_f32_e32 v0, v43, v15
	v_cvt_pk_bf16_f32 v0, v0, s0
	global_store_short v[4:5], v0, off offset:3072
	v_mul_f32_e32 v0, v27, v15
	v_cvt_pk_bf16_f32 v0, v0, s0
	s_mov_b32 s2, 0xc000
	v_rcp_f32_e32 v49, v75
	global_store_short v[4:5], v0, off offset:3136
	v_mul_f32_e32 v0, v44, v48
	v_add_co_u32_e32 v4, vcc, s2, v2
	v_cvt_pk_bf16_f32 v0, v0, s0
	s_nop 0
	v_addc_co_u32_e32 v5, vcc, 0, v3, vcc
	global_store_short v[4:5], v0, off offset:1024
	v_mul_f32_e32 v0, v28, v48
	v_cvt_pk_bf16_f32 v0, v0, s0
	v_rcp_f32_e32 v50, v76
	global_store_short v[4:5], v0, off offset:1088
	v_mul_f32_e32 v0, v45, v49
	v_cvt_pk_bf16_f32 v0, v0, s0
	global_store_short v[4:5], v0, off offset:3072
	v_mul_f32_e32 v0, v29, v49
	v_cvt_pk_bf16_f32 v0, v0, s0
	s_mov_b32 s2, 0xd000
	v_rcp_f32_e32 v51, v77
	global_store_short v[4:5], v0, off offset:3136
	v_mul_f32_e32 v0, v46, v50
	v_add_co_u32_e32 v2, vcc, s2, v2
	v_cvt_pk_bf16_f32 v0, v0, s0
	s_nop 0
	v_addc_co_u32_e32 v3, vcc, 0, v3, vcc
	global_store_short v[2:3], v0, off offset:1024
	v_mul_f32_e32 v0, v30, v50
	v_cvt_pk_bf16_f32 v0, v0, s0
	global_store_short v[2:3], v0, off offset:1088
	v_mul_f32_e32 v0, v47, v51
	v_cvt_pk_bf16_f32 v0, v0, s0
	global_store_short v[2:3], v0, off offset:3072
	v_mul_f32_e32 v0, v31, v51
	v_cvt_pk_bf16_f32 v0, v0, s0
	global_store_short v[2:3], v0, off offset:3136
	s_waitcnt lgkmcnt(0)
	s_barrier

.LBB0_851:
	s_or_b64 exec, exec, s[6:7]
	ds_swizzle_b32 v3, v0 offset:swizzle(SWAP,1)
	v_max_f32_e32 v0, v0, v0
	s_ashr_i32 s90, s2, 7
	s_ashr_i32 s91, s2, 6
	s_lshl_b32 s6, s45, 7
	s_waitcnt lgkmcnt(0)
	v_max_f32_e32 v3, v3, v3
	v_max_f32_e32 v0, v0, v3
	ds_swizzle_b32 v3, v0 offset:swizzle(SWAP,2)
	s_lshl_b32 s2, s90, 5
	s_add_i32 s10, s6, s2
	s_add_i32 s53, s10, 0xffffff80
	s_lshl_b32 s2, s78, 10
	s_waitcnt lgkmcnt(0)
	v_max_f32_e32 v3, v3, v3
	s_and_b32 s60, s91, 1
	v_max_f32_e32 v0, v0, v3
	s_and_b32 s11, s2, 0x7ffff000
	s_lshl_b32 s79, s3, 7
	s_lshr_b32 s71, s6, 6
	s_ashr_i32 s2, s53, 6
	s_ashr_i32 s6, s53, 31
	ds_swizzle_b32 v3, v0 offset:swizzle(SWAP,4)
	s_add_u32 s46, s53, s11
	v_and_b32_e32 v130, 31, v2
	s_addc_u32 s47, s6, 0
	v_or_b32_e32 v4, s46, v130
	v_mov_b32_e32 v5, s47
	v_lshlrev_b64 v[4:5], 11, v[4:5]
	v_lshl_add_u64 v[4:5], s[94:95], 0, v[4:5]
	s_lshl_b32 s50, s3, 8
	v_lshrrev_b32_e32 v131, 5, v133
	s_waitcnt lgkmcnt(0)
	v_max_f32_e32 v3, v3, v3
	v_lshl_add_u64 v[4:5], v[4:5], 0, s[50:51]
	s_lshl_b32 s6, s60, 7
	s_mov_b32 s7, s51
	v_max_f32_e32 v3, v0, v3
	v_lshl_add_u64 v[4:5], v[4:5], 0, s[6:7]
	v_lshlrev_b32_e32 v0, 4, v131
	v_lshl_add_u64 v[4:5], v[4:5], 0, v[0:1]
	v_or_b32_e32 v0, s11, v133
	global_load_dwordx4 v[114:117], v[4:5], off
	global_load_dwordx4 v[118:121], v[4:5], off offset:32
	global_load_dwordx4 v[122:125], v[4:5], off offset:64
	global_load_dwordx4 v[126:129], v[4:5], off offset:96
	v_lshlrev_b64 v[4:5], 11, v[0:1]
	s_lshl_b32 s6, s91, 3
	v_lshl_add_u64 v[4:5], s[96:97], 0, v[4:5]
	s_ashr_i32 s7, s6, 31
	s_lshl_b32 s72, s91, 10
	v_lshl_add_u64 v[4:5], v[4:5], 0, s[50:51]
	s_lshl_b64 s[8:9], s[6:7], 1
	s_add_i32 s3, s72, 0
	v_lshl_add_u64 v[4:5], v[4:5], 0, s[8:9]
	s_mov_b32 m0, s3
	s_lshl_b32 s7, s91, 4
	global_load_lds_dwordx4 v[4:5], off
	v_lshl_add_u64 v[4:5], v[4:5], 0, s[54:55]
	s_add_i32 m0, s3, 0x2000
	s_and_b32 s7, s7, 48
	v_lshrrev_b32_e32 v11, 2, v133
	global_load_lds_dwordx4 v[4:5], off
	v_or_b32_e32 v4, s7, v11
	v_or_b32_e32 v4, s11, v4
	v_mov_b32_e32 v5, v1
	v_lshlrev_b64 v[4:5], 11, v[4:5]
	s_add_i32 m0, s3, 0x4000
	s_add_i32 s3, s91, 8
	v_lshl_add_u64 v[4:5], s[56:57], 0, v[4:5]
	s_and_b32 s84, s6, 0xffffffe0
	v_lshlrev_b32_e32 v8, 3, v133
	s_lshl_b32 s6, s3, 3
	v_lshl_add_u64 v[4:5], v[4:5], 0, s[50:51]
	s_ashr_i32 s85, s84, 31
	v_and_b32_e32 v132, 24, v8
	s_and_b32 s86, s6, 0xffffffe0
	v_lshl_add_u64 v[6:7], s[84:85], 1, v[4:5]
	v_lshlrev_b32_e32 v8, 1, v132
	v_mov_b32_e32 v9, v1
	s_ashr_i32 s87, s86, 31
	s_lshl_b32 s76, s3, 10
	v_lshl_add_u64 v[6:7], v[6:7], 0, v[8:9]
	v_lshl_add_u64 v[4:5], s[86:87], 1, v[4:5]
	s_add_i32 s3, s76, 0
	global_load_lds_dwordx4 v[6:7], off
	v_lshl_add_u64 v[4:5], v[4:5], 0, v[8:9]
	s_add_i32 m0, s3, 0x4000
	ds_swizzle_b32 v10, v3 offset:swizzle(SWAP,8)
	global_load_lds_dwordx4 v[4:5], off
	s_lshl_b32 s92, s60, 13
	s_max_u32 s93, s71, 1
	s_waitcnt lgkmcnt(0)
	v_max_f32_e32 v4, v10, v10
	v_max_f32_e32 v3, v3, v4
	ds_swizzle_b32 v4, v3 offset:swizzle(SWAP,16)
	s_add_u32 s3, s96, s50
	s_addc_u32 s6, s97, 0
	s_add_u32 s88, s3, s8
	s_addc_u32 s89, s6, s9
	s_waitcnt lgkmcnt(0)
	v_max_f32_e32 v4, v4, v4
	v_max_f32_e32 v3, v3, v4
	v_mov_b32_e32 v4, v3
	s_nop 1
	v_permlane32_swap_b32_e32 v3, v4
	v_max_f32_e32 v4, v4, v4
	v_max_f32_e32 v3, v3, v3
	v_max_f32_e32 v3, v3, v4
	v_add_f32_e32 v3, s80, v3
	v_xor_b32_e32 v66, 0x80000000, v3
	v_lshlrev_b32_e32 v3, 2, v131
	v_lshrrev_b32_e32 v2, 2, v2
	s_add_u32 s74, s56, s50
	v_and_or_b32 v2, v2, 3, v3
	s_addc_u32 s75, s57, 0
	s_addk_i32 s10, 0xff45
	v_lshlrev_b32_e32 v139, 6, v2
	v_add_u32_e32 v2, s10, v130
	v_lshlrev_b32_e32 v4, 1, v133
	v_sub_u32_e32 v140, v2, v3
	v_or_b32_e32 v2, s11, v11
	v_mov_b32_e32 v14, v1
	v_mov_b32_e32 v15, v1
	v_and_b32_e32 v138, 32, v4
	v_or3_b32 v141, v2, s7, 64
	v_or_b32_e32 v142, 64, v0
	v_mov_b32_e32 v0, v1
	v_mov_b32_e32 v2, v1
	v_mov_b32_e32 v3, v1
	v_mov_b32_e32 v4, v1
	v_mov_b32_e32 v5, v1
	v_mov_b32_e32 v6, v1
	v_mov_b32_e32 v7, v1
	v_mov_b32_e32 v8, v1
	v_mov_b32_e32 v10, v1
	v_mov_b32_e32 v11, v1
	v_mov_b32_e32 v12, v1
	v_mov_b32_e32 v13, v1
	v_mov_b64_e32 v[64:65], v[14:15]
	v_mov_b64_e32 v[48:49], v[14:15]
	v_mov_b64_e32 v[32:33], v[14:15]
	v_mov_b64_e32 v[62:63], v[12:13]
	v_mov_b64_e32 v[60:61], v[10:11]
	v_mov_b64_e32 v[58:59], v[8:9]
	v_mov_b64_e32 v[56:57], v[6:7]
	v_mov_b64_e32 v[54:55], v[4:5]
	v_mov_b64_e32 v[52:53], v[2:3]
	v_mov_b64_e32 v[50:51], v[0:1]
	v_mov_b64_e32 v[46:47], v[12:13]
	v_mov_b64_e32 v[44:45], v[10:11]
	v_mov_b64_e32 v[42:43], v[8:9]
	v_mov_b64_e32 v[40:41], v[6:7]
	v_mov_b64_e32 v[38:39], v[4:5]
	v_mov_b64_e32 v[36:37], v[2:3]
	v_mov_b64_e32 v[34:35], v[0:1]
	v_mov_b64_e32 v[30:31], v[12:13]
	v_mov_b64_e32 v[28:29], v[10:11]
	v_mov_b64_e32 v[26:27], v[8:9]
	v_mov_b64_e32 v[24:25], v[6:7]
	v_mov_b64_e32 v[22:23], v[4:5]
	v_mov_b64_e32 v[20:21], v[2:3]
	v_mov_b64_e32 v[18:19], v[0:1]
	v_mov_b64_e32 v[16:17], v[14:15]
	v_lshlrev_b32_e32 v136, 10, v131
	v_lshlrev_b32_e32 v137, 4, v130
	v_mov_b32_e32 v67, v66
	v_mov_b32_e32 v68, v66
	v_mov_b32_e32 v69, v66
	v_mov_b32_e32 v70, v66
	v_mov_b32_e32 v71, v66
	v_mov_b32_e32 v72, v66
	v_mov_b32_e32 v73, v66
	v_mov_b32_e32 v74, v66
	v_mov_b32_e32 v75, v66
	v_mov_b32_e32 v76, v66
	v_mov_b32_e32 v77, v66
	v_mov_b32_e32 v78, v66
	v_mov_b32_e32 v79, v66
	v_mov_b32_e32 v80, v66
	v_mov_b32_e32 v81, v66
	s_mov_b32 s50, 0
	v_mov_b64_e32 v[14:15], v[12:13]
	v_mov_b64_e32 v[12:13], v[10:11]
	v_mov_b64_e32 v[10:11], v[8:9]
	v_mov_b64_e32 v[8:9], v[6:7]
	v_mov_b64_e32 v[6:7], v[4:5]
	v_mov_b64_e32 v[4:5], v[2:3]
	v_mov_b64_e32 v[2:3], v[0:1]
	s_mov_b32 s6, 0
	s_waitcnt vmcnt(0)
	s_cmp_gt_u32 s91, 3
	s_cbranch_scc0 .Ld_np
	s_setprio 1
.Ld_np:
.LBB0_852:
	s_waitcnt vmcnt(0)
	s_and_b32 s7, s6, 1
	s_add_i32 s3, s6, 1
	s_cmp_ge_u32 s3, s71
	s_barrier
	s_cbranch_scc1 .LBB0_855
	s_lshl_b32 s8, s7, 15
	s_xor_b32 s8, s8, 0x8000
	s_add_i32 s8, s8, 0
	v_add_u32_e32 v0, s50, v142
	v_lshlrev_b64 v[82:83], 11, v[0:1]
	s_add_i32 s9, s8, s72
	v_lshl_add_u64 v[82:83], s[88:89], 0, v[82:83]
	s_mov_b32 m0, s9
	v_add_u32_e32 v0, s50, v141
	global_load_lds_dwordx4 v[82:83], off
	v_lshl_add_u64 v[82:83], v[82:83], 0, s[54:55]
	s_add_i32 m0, s9, 0x2000
	s_add_i32 s8, s8, s76
	global_load_lds_dwordx4 v[82:83], off
	v_lshlrev_b64 v[82:83], 11, v[0:1]
	v_lshl_add_u64 v[82:83], s[74:75], 0, v[82:83]
	v_lshl_add_u64 v[84:85], s[84:85], 1, v[82:83]
	v_lshlrev_b32_e32 v0, 1, v132
	v_lshl_add_u64 v[84:85], v[84:85], 0, v[0:1]
	s_add_i32 m0, s9, 0x4000
	v_lshl_add_u64 v[82:83], s[86:87], 1, v[82:83]
	global_load_lds_dwordx4 v[84:85], off
	v_lshl_add_u64 v[82:83], v[82:83], 0, v[0:1]
	s_add_i32 m0, s8, 0x4000
	s_nop 0
	global_load_lds_dwordx4 v[82:83], off
	s_cmp_gt_i32 s6, s2
	s_cbranch_scc0 .LBB0_856

.LBB0_865:
	s_setprio 0
	s_lshl_b32 s2, s91, 7
	s_waitcnt lgkmcnt(0)
	s_add_i32 s2, s2, 0
	v_mov_b32_e32 v0, v135
	s_add_i32 s2, s2, 0x10400
	s_nop 0
	v_permlane32_swap_b32_e32 v135, v0
	s_and_saveexec_b64 s[6:7], vcc
	s_cbranch_execz .LBB0_867
	v_add_f32_e32 v0, v135, v0
	v_rcp_f32_e32 v0, v0
	v_lshl_add_u32 v66, v130, 2, s2
	ds_write_b32 v66, v0

.LBB0_874:
	s_lshl_b32 s3, s3, 6
	s_lshl_b32 s3, s3, 1
	s_lshr_b32 s41, s11, 6
	s_ashr_i32 s53, s40, 6
	s_add_i32 s11, 0, 0x10000
	s_lshl_b64 s[6:7], s[6:7], 1
	s_waitcnt vmcnt(0)
	v_subrev_f32_e32 v48, s81, v4
	v_or_b32_e32 v4, s10, v5
	s_add_u32 s10, s96, s6
	v_lshl_add_u32 v137, v3, 2, s11
	v_or_b32_e32 v138, s14, v4
	v_lshlrev_b32_e32 v4, 2, v135
	v_lshl_add_u32 v139, v135, 4, s11
	v_lshrrev_b32_e32 v2, 2, v2
	s_addc_u32 s11, s97, s7
	s_lshl_b64 s[6:7], s[8:9], 1
	v_and_or_b32 v2, v2, 3, v4
	s_add_u32 s6, s56, s6
	v_lshlrev_b32_e32 v3, 1, v3
	v_lshlrev_b32_e32 v143, 6, v2
	s_addc_u32 s7, s57, s7
	v_add_u32_e32 v2, s40, v136
	v_and_b32_e32 v142, 32, v3
	v_sub_u32_e32 v144, v2, v4
	v_lshl_add_u64 v[2:3], s[6:7], 0, v[0:1]
	s_or_b32 s50, s3, 0x400
	v_mov_b32_e32 v14, v1
	v_mov_b32_e32 v15, v1
	s_add_u32 s88, s10, s50
	v_lshl_add_u64 v[132:133], v[2:3], 0, s[50:51]
	v_mov_b32_e32 v0, v1
	v_mov_b32_e32 v2, v1
	v_mov_b32_e32 v3, v1
	v_mov_b32_e32 v4, v1
	v_mov_b32_e32 v5, v1
	v_mov_b32_e32 v6, v1
	v_mov_b32_e32 v7, v1
	v_mov_b32_e32 v8, v1
	v_mov_b32_e32 v9, v1
	v_mov_b32_e32 v10, v1
	v_mov_b32_e32 v11, v1
	v_mov_b32_e32 v12, v1
	v_mov_b32_e32 v13, v1
	v_mov_b64_e32 v[46:47], v[14:15]
	v_mov_b64_e32 v[30:31], v[14:15]
	v_mov_b64_e32 v[76:77], v[14:15]
	v_mov_b32_e32 v49, v48
	v_mov_b32_e32 v50, v48
	v_mov_b32_e32 v51, v48
	v_mov_b32_e32 v52, v48
	v_mov_b32_e32 v53, v48
	v_mov_b32_e32 v54, v48
	v_mov_b32_e32 v55, v48
	v_mov_b32_e32 v56, v48
	v_mov_b32_e32 v57, v48
	v_mov_b32_e32 v58, v48
	v_mov_b32_e32 v59, v48
	v_mov_b32_e32 v60, v48
	v_mov_b32_e32 v61, v48
	v_lshlrev_b32_e32 v140, 10, v135
	v_lshlrev_b32_e32 v141, 4, v136
	s_addc_u32 s89, s11, 0
	s_mov_b32 s6, 0
	s_mov_b32 s60, 63
	v_mov_b32_e32 v145, 0
	v_mov_b32_e32 v78, v48
	v_mov_b32_e32 v79, v48
	v_mov_b64_e32 v[44:45], v[12:13]
	v_mov_b64_e32 v[42:43], v[10:11]
	v_mov_b64_e32 v[40:41], v[8:9]
	v_mov_b64_e32 v[38:39], v[6:7]
	v_mov_b64_e32 v[36:37], v[4:5]
	v_mov_b64_e32 v[34:35], v[2:3]
	v_mov_b64_e32 v[32:33], v[0:1]
	v_mov_b64_e32 v[28:29], v[12:13]
	v_mov_b64_e32 v[26:27], v[10:11]
	v_mov_b64_e32 v[24:25], v[8:9]
	v_mov_b64_e32 v[22:23], v[6:7]
	v_mov_b64_e32 v[20:21], v[4:5]
	v_mov_b64_e32 v[18:19], v[2:3]
	v_mov_b64_e32 v[16:17], v[0:1]
	v_mov_b64_e32 v[74:75], v[12:13]
	v_mov_b64_e32 v[72:73], v[10:11]
	v_mov_b64_e32 v[70:71], v[8:9]
	v_mov_b64_e32 v[68:69], v[6:7]
	v_mov_b64_e32 v[66:67], v[4:5]
	v_mov_b64_e32 v[64:65], v[2:3]
	v_mov_b64_e32 v[62:63], v[0:1]
	s_cmp_gt_u32 s15, 0xff
	s_cbranch_scc0 .Lf_np
	s_setprio 1
.Lf_np:
.LBB0_875:
	s_and_b32 s72, s6, 1
	s_add_i32 s71, s6, 1
	s_waitcnt vmcnt(0)
	s_cmp_ge_u32 s71, s41
	s_cselect_b64 s[78:79], -1, 0
	s_and_b64 vcc, exec, s[78:79]
	s_waitcnt lgkmcnt(0)
	s_barrier
	s_cbranch_vccnz .LBB0_878
	s_lshl_b32 s7, s72, 15
	s_add_i32 s50, s60, 1
	s_xor_b32 s7, s7, 0x8000
	v_add_u32_e32 v0, s50, v128
	v_lshlrev_b64 v[2:3], 11, v[0:1]
	s_add_i32 s7, s2, s7
	v_lshl_add_u64 v[2:3], s[88:89], 0, v[2:3]
	s_mov_b32 m0, s7
	v_add_u32_e32 v0, s50, v138
	global_load_lds_dwordx4 v[2:3], off
	v_lshlrev_b64 v[2:3], 11, v[0:1]
	v_lshl_add_u64 v[2:3], v[132:133], 0, v[2:3]
	s_add_i32 m0, s7, 0x4000
	s_andn2_b64 vcc, exec, s[86:87]
	global_load_lds_dwordx4 v[2:3], off
	s_cbranch_vccnz .LBB0_878
	v_lshl_add_u64 v[2:3], s[50:51], 2, v[130:131]
	global_load_dword v145, v[2:3], off
